# fft1: all 64 twiddle loads issued before the MFMA stage (relocated registers) instead of two serialized batches after it
# baseline (speedup 1.0000x reference)
; __device__ __forceinline__ void fft1_phase(KP P, int l) {
;     ...
;     for (int it = bid_; it < 256; it += gridDim.x) {
;         const int b = it >> 7, l2 = it & 127, ch = 32 * w + r32;
;         const unsigned* vsrc = (const unsigned*)(ws + WS_VS) + ((size_t)(b * SEQ + l2 + 512 * hi)) * 256 + ch;
;         u32x4_t bfr[8];
; #pragma unroll
;         for (int s = 0; s < 8; ++s)
; #pragma unroll
;             for (int j = 0; j < 4; ++j) bfr[s][j] = vsrc[(size_t)(128 * (8 * s + j)) * 256];
;         f32x16 acc[4] = {};
; #pragma unroll
;         for (int s = 0; s < 8; ++s) {
;             const bf16x8_t bf = __builtin_bit_cast(bf16x8_t, bfr[s]);
; #pragma unroll
;             for (int mt = 0; mt < 4; ++mt) { const bf16x8_t af = *(const bf16x8_t*)(D1 + (32 * mt + r32) * 128 + 16 * s + 8 * hi);
;     ...
;                     const int k1 = 16 * mt + 4 * rq + 2 * hi + e; const int idx = k1 * l2;
;                     const float ct = TAB[TAB_COS + idx], st = TAB[TAB_COS + ((idx - 2048) & 8191)];
.Lf1_item:
	s_cmpk_lt_i32 s26, 0x100
	s_cbranch_scc0 .Lf1_done
	s_lshr_b32 s2, s26, 7
	s_and_b32 s3, s26, 0x7f
	s_lshl_b32 s14, s2, 13
	s_add_u32 s14, s14, s3
	s_lshl_b32 s14, s14, 10
	s_add_u32 s14, s14, 0x9100000
	s_add_u32 s14, s12, s14
	s_addc_u32 s15, s13, 0
	global_load_dword v64, v170, s[14:15]
	s_add_u32 s14, s14, 0x20000
	s_addc_u32 s15, s15, 0
	global_load_dword v65, v170, s[14:15]
	s_add_u32 s14, s14, 0x20000
	s_addc_u32 s15, s15, 0
	global_load_dword v66, v170, s[14:15]
	s_add_u32 s14, s14, 0x20000
	s_addc_u32 s15, s15, 0
	global_load_dword v67, v170, s[14:15]
	s_add_u32 s14, s14, 0xa0000
	s_addc_u32 s15, s15, 0
	global_load_dword v68, v170, s[14:15]
	s_add_u32 s14, s14, 0x20000
	s_addc_u32 s15, s15, 0
	global_load_dword v69, v170, s[14:15]
	s_add_u32 s14, s14, 0x20000
	s_addc_u32 s15, s15, 0
	global_load_dword v70, v170, s[14:15]
	s_add_u32 s14, s14, 0x20000
	s_addc_u32 s15, s15, 0
	global_load_dword v71, v170, s[14:15]
	s_add_u32 s14, s14, 0xa0000
	s_addc_u32 s15, s15, 0
	global_load_dword v72, v170, s[14:15]
	s_add_u32 s14, s14, 0x20000
	s_addc_u32 s15, s15, 0
	global_load_dword v73, v170, s[14:15]
	s_add_u32 s14, s14, 0x20000
	s_addc_u32 s15, s15, 0
	global_load_dword v74, v170, s[14:15]
	s_add_u32 s14, s14, 0x20000
	s_addc_u32 s15, s15, 0
	global_load_dword v75, v170, s[14:15]
	s_add_u32 s14, s14, 0xa0000
	s_addc_u32 s15, s15, 0
	global_load_dword v76, v170, s[14:15]
	s_add_u32 s14, s14, 0x20000
	s_addc_u32 s15, s15, 0
	global_load_dword v77, v170, s[14:15]
	s_add_u32 s14, s14, 0x20000
	s_addc_u32 s15, s15, 0
	global_load_dword v78, v170, s[14:15]
	s_add_u32 s14, s14, 0x20000
	s_addc_u32 s15, s15, 0
	global_load_dword v79, v170, s[14:15]
	s_add_u32 s14, s14, 0xa0000
	s_addc_u32 s15, s15, 0
	global_load_dword v80, v170, s[14:15]
	s_add_u32 s14, s14, 0x20000
	s_addc_u32 s15, s15, 0
	global_load_dword v81, v170, s[14:15]
	s_add_u32 s14, s14, 0x20000
	s_addc_u32 s15, s15, 0
	global_load_dword v82, v170, s[14:15]
	s_add_u32 s14, s14, 0x20000
	s_addc_u32 s15, s15, 0
	global_load_dword v83, v170, s[14:15]
	s_add_u32 s14, s14, 0xa0000
	s_addc_u32 s15, s15, 0
	global_load_dword v84, v170, s[14:15]
	s_add_u32 s14, s14, 0x20000
	s_addc_u32 s15, s15, 0
	global_load_dword v85, v170, s[14:15]
	s_add_u32 s14, s14, 0x20000
	s_addc_u32 s15, s15, 0
	global_load_dword v86, v170, s[14:15]
	s_add_u32 s14, s14, 0x20000
	s_addc_u32 s15, s15, 0
	global_load_dword v87, v170, s[14:15]
	s_add_u32 s14, s14, 0xa0000
	s_addc_u32 s15, s15, 0
	global_load_dword v88, v170, s[14:15]
	s_add_u32 s14, s14, 0x20000
	s_addc_u32 s15, s15, 0
	global_load_dword v89, v170, s[14:15]
	s_add_u32 s14, s14, 0x20000
	s_addc_u32 s15, s15, 0
	global_load_dword v90, v170, s[14:15]
	s_add_u32 s14, s14, 0x20000
	s_addc_u32 s15, s15, 0
	global_load_dword v91, v170, s[14:15]
	s_add_u32 s14, s14, 0xa0000
	s_addc_u32 s15, s15, 0
	global_load_dword v92, v170, s[14:15]
	s_add_u32 s14, s14, 0x20000
	s_addc_u32 s15, s15, 0
	global_load_dword v93, v170, s[14:15]
	s_add_u32 s14, s14, 0x20000
	s_addc_u32 s15, s15, 0
	global_load_dword v94, v170, s[14:15]
	s_add_u32 s14, s14, 0x20000
	s_addc_u32 s15, s15, 0
	global_load_dword v95, v170, s[14:15]
	s_add_u32 s14, s14, 0xa0000
	s_addc_u32 s15, s15, 0
	s_add_u32 s2, s12, 0xc028000
	s_addc_u32 s3, s13, 0
	global_load_dwordx4 v[96:99], v171, s[2:3] offset:0
	global_load_dwordx4 v[100:103], v172, s[2:3] offset:0
	global_load_dwordx4 v[104:107], v173, s[2:3] offset:0
	global_load_dwordx4 v[108:111], v174, s[2:3] offset:0
	global_load_dwordx4 v[112:115], v171, s[2:3] offset:32
	global_load_dwordx4 v[116:119], v172, s[2:3] offset:32
	global_load_dwordx4 v[120:123], v173, s[2:3] offset:32
	global_load_dwordx4 v[124:127], v174, s[2:3] offset:32
	global_load_dwordx4 v[128:131], v171, s[2:3] offset:64
	global_load_dwordx4 v[132:135], v172, s[2:3] offset:64
	global_load_dwordx4 v[136:139], v173, s[2:3] offset:64
	global_load_dwordx4 v[140:143], v174, s[2:3] offset:64
	global_load_dwordx4 v[148:151], v171, s[2:3] offset:96
	global_load_dwordx4 v[152:155], v172, s[2:3] offset:96
	global_load_dwordx4 v[156:159], v173, s[2:3] offset:96
	global_load_dwordx4 v[160:163], v174, s[2:3] offset:96
	s_and_b32 s3, s26, 0x7f
	v_mul_u32_u24_e32 v177, s3, v176
	v_lshlrev_b32_e32 v177, 1, v177
	s_mul_i32 s2, s3, 0
	v_add_u32_e32 v178, s2, v177
	v_add_u32_e32 v179, 0xfffff800, v178
	v_lshlrev_b32_e32 v178, 2, v178
	v_and_b32_e32 v179, 0x1fff, v179
	v_lshlrev_b32_e32 v179, 2, v179
	global_load_dword v182, v178, s[6:7]
	global_load_dword v226, v179, s[6:7]
	s_mul_i32 s2, s3, 1
	v_add_u32_e32 v178, s2, v177
	v_add_u32_e32 v179, 0xfffff800, v178
	v_lshlrev_b32_e32 v178, 2, v178
	v_and_b32_e32 v179, 0x1fff, v179
	v_lshlrev_b32_e32 v179, 2, v179
	global_load_dword v183, v178, s[6:7]
	global_load_dword v227, v179, s[6:7]
	s_mul_i32 s2, s3, 4
	v_add_u32_e32 v178, s2, v177
	v_add_u32_e32 v179, 0xfffff800, v178
	v_lshlrev_b32_e32 v178, 2, v178
	v_and_b32_e32 v179, 0x1fff, v179
	v_lshlrev_b32_e32 v179, 2, v179
	global_load_dword v184, v178, s[6:7]
	global_load_dword v228, v179, s[6:7]
	s_mul_i32 s2, s3, 5
	v_add_u32_e32 v178, s2, v177
	v_add_u32_e32 v179, 0xfffff800, v178
	v_lshlrev_b32_e32 v178, 2, v178
	v_and_b32_e32 v179, 0x1fff, v179
	v_lshlrev_b32_e32 v179, 2, v179
	global_load_dword v185, v178, s[6:7]
	global_load_dword v229, v179, s[6:7]
	s_mul_i32 s2, s3, 8
	v_add_u32_e32 v178, s2, v177
	v_add_u32_e32 v179, 0xfffff800, v178
	v_lshlrev_b32_e32 v178, 2, v178
	v_and_b32_e32 v179, 0x1fff, v179
	v_lshlrev_b32_e32 v179, 2, v179
	global_load_dword v186, v178, s[6:7]
	global_load_dword v230, v179, s[6:7]
	s_mul_i32 s2, s3, 9
	v_add_u32_e32 v178, s2, v177
	v_add_u32_e32 v179, 0xfffff800, v178
; __device__ __forceinline__ void fft1_phase(KP P, int l) {
;     ...
;                     const int k1 = 16 * mt + 4 * rq + 2 * hi + e; const int idx = k1 * l2;
;                     const float ct = TAB[TAB_COS + idx], st = TAB[TAB_COS + ((idx - 2048) & 8191)];
	v_lshlrev_b32_e32 v178, 2, v178
	v_and_b32_e32 v179, 0x1fff, v179
	v_lshlrev_b32_e32 v179, 2, v179
	global_load_dword v187, v178, s[6:7]
	global_load_dword v231, v179, s[6:7]
	s_mul_i32 s2, s3, 12
	v_add_u32_e32 v178, s2, v177
	v_add_u32_e32 v179, 0xfffff800, v178
	v_lshlrev_b32_e32 v178, 2, v178
	v_and_b32_e32 v179, 0x1fff, v179
	v_lshlrev_b32_e32 v179, 2, v179
	global_load_dword v188, v178, s[6:7]
	global_load_dword v232, v179, s[6:7]
	s_mul_i32 s2, s3, 13
	v_add_u32_e32 v178, s2, v177
	v_add_u32_e32 v179, 0xfffff800, v178
	v_lshlrev_b32_e32 v178, 2, v178
	v_and_b32_e32 v179, 0x1fff, v179
	v_lshlrev_b32_e32 v179, 2, v179
	global_load_dword v189, v178, s[6:7]
	global_load_dword v233, v179, s[6:7]
	s_mul_i32 s2, s3, 16
	v_add_u32_e32 v178, s2, v177
	v_add_u32_e32 v179, 0xfffff800, v178
	v_lshlrev_b32_e32 v178, 2, v178
	v_and_b32_e32 v179, 0x1fff, v179
	v_lshlrev_b32_e32 v179, 2, v179
	global_load_dword v190, v178, s[6:7]
	global_load_dword v234, v179, s[6:7]
	s_mul_i32 s2, s3, 17
	v_add_u32_e32 v178, s2, v177
	v_add_u32_e32 v179, 0xfffff800, v178
	v_lshlrev_b32_e32 v178, 2, v178
	v_and_b32_e32 v179, 0x1fff, v179
	v_lshlrev_b32_e32 v179, 2, v179
	global_load_dword v191, v178, s[6:7]
	global_load_dword v235, v179, s[6:7]
	s_mul_i32 s2, s3, 20
	v_add_u32_e32 v178, s2, v177
	v_add_u32_e32 v179, 0xfffff800, v178
	v_lshlrev_b32_e32 v178, 2, v178
	v_and_b32_e32 v179, 0x1fff, v179
	v_lshlrev_b32_e32 v179, 2, v179
	global_load_dword v192, v178, s[6:7]
	global_load_dword v236, v179, s[6:7]
	s_mul_i32 s2, s3, 21
	v_add_u32_e32 v178, s2, v177
	v_add_u32_e32 v179, 0xfffff800, v178
	v_lshlrev_b32_e32 v178, 2, v178
	v_and_b32_e32 v179, 0x1fff, v179
	v_lshlrev_b32_e32 v179, 2, v179
	global_load_dword v193, v178, s[6:7]
	global_load_dword v237, v179, s[6:7]
	s_mul_i32 s2, s3, 24
	v_add_u32_e32 v178, s2, v177
	v_add_u32_e32 v179, 0xfffff800, v178
	v_lshlrev_b32_e32 v178, 2, v178
	v_and_b32_e32 v179, 0x1fff, v179
	v_lshlrev_b32_e32 v179, 2, v179
	global_load_dword v194, v178, s[6:7]
	global_load_dword v238, v179, s[6:7]
	s_mul_i32 s2, s3, 25
	v_add_u32_e32 v178, s2, v177
	v_add_u32_e32 v179, 0xfffff800, v178
	v_lshlrev_b32_e32 v178, 2, v178
	v_and_b32_e32 v179, 0x1fff, v179
	v_lshlrev_b32_e32 v179, 2, v179
	global_load_dword v195, v178, s[6:7]
	global_load_dword v239, v179, s[6:7]
	s_mul_i32 s2, s3, 28
	v_add_u32_e32 v178, s2, v177
	v_add_u32_e32 v179, 0xfffff800, v178
	v_lshlrev_b32_e32 v178, 2, v178
	v_and_b32_e32 v179, 0x1fff, v179
	v_lshlrev_b32_e32 v179, 2, v179
	global_load_dword v196, v178, s[6:7]
	global_load_dword v240, v179, s[6:7]
	s_mul_i32 s2, s3, 29
	v_add_u32_e32 v178, s2, v177
	v_add_u32_e32 v179, 0xfffff800, v178
	v_lshlrev_b32_e32 v178, 2, v178
	v_and_b32_e32 v179, 0x1fff, v179
	v_lshlrev_b32_e32 v179, 2, v179
	global_load_dword v197, v178, s[6:7]
	global_load_dword v241, v179, s[6:7]
	s_mul_i32 s2, s3, 32
	v_add_u32_e32 v178, s2, v177
	v_add_u32_e32 v179, 0xfffff800, v178
	v_lshlrev_b32_e32 v178, 2, v178
	v_and_b32_e32 v179, 0x1fff, v179
	v_lshlrev_b32_e32 v179, 2, v179
	global_load_dword v200, v178, s[6:7]
	global_load_dword v242, v179, s[6:7]
	s_mul_i32 s2, s3, 33
	v_add_u32_e32 v178, s2, v177
	v_add_u32_e32 v179, 0xfffff800, v178
	v_lshlrev_b32_e32 v178, 2, v178
	v_and_b32_e32 v179, 0x1fff, v179
	v_lshlrev_b32_e32 v179, 2, v179
	global_load_dword v201, v178, s[6:7]
	global_load_dword v243, v179, s[6:7]
	s_mul_i32 s2, s3, 36
	v_add_u32_e32 v178, s2, v177
	v_add_u32_e32 v179, 0xfffff800, v178
	v_lshlrev_b32_e32 v178, 2, v178
	v_and_b32_e32 v179, 0x1fff, v179
	v_lshlrev_b32_e32 v179, 2, v179
	global_load_dword v202, v178, s[6:7]
	global_load_dword v244, v179, s[6:7]
	s_mul_i32 s2, s3, 37
	v_add_u32_e32 v178, s2, v177
	v_add_u32_e32 v179, 0xfffff800, v178
	v_lshlrev_b32_e32 v178, 2, v178
	v_and_b32_e32 v179, 0x1fff, v179
	v_lshlrev_b32_e32 v179, 2, v179
	global_load_dword v203, v178, s[6:7]
	global_load_dword v245, v179, s[6:7]
	s_mul_i32 s2, s3, 40
	v_add_u32_e32 v178, s2, v177
	v_add_u32_e32 v179, 0xfffff800, v178
	v_lshlrev_b32_e32 v178, 2, v178
	v_and_b32_e32 v179, 0x1fff, v179
	v_lshlrev_b32_e32 v179, 2, v179
	global_load_dword v204, v178, s[6:7]
	global_load_dword v246, v179, s[6:7]
	s_mul_i32 s2, s3, 41
	v_add_u32_e32 v178, s2, v177
	v_add_u32_e32 v179, 0xfffff800, v178
	v_lshlrev_b32_e32 v178, 2, v178
	v_and_b32_e32 v179, 0x1fff, v179
	v_lshlrev_b32_e32 v179, 2, v179
	global_load_dword v205, v178, s[6:7]
	global_load_dword v247, v179, s[6:7]
	s_mul_i32 s2, s3, 44
	v_add_u32_e32 v178, s2, v177
	v_add_u32_e32 v179, 0xfffff800, v178
	v_lshlrev_b32_e32 v178, 2, v178
	v_and_b32_e32 v179, 0x1fff, v179
	v_lshlrev_b32_e32 v179, 2, v179
	global_load_dword v206, v178, s[6:7]
	global_load_dword v248, v179, s[6:7]
	s_mul_i32 s2, s3, 45
	v_add_u32_e32 v178, s2, v177
	v_add_u32_e32 v179, 0xfffff800, v178
	v_lshlrev_b32_e32 v178, 2, v178
	v_and_b32_e32 v179, 0x1fff, v179
	v_lshlrev_b32_e32 v179, 2, v179
	global_load_dword v207, v178, s[6:7]
	global_load_dword v249, v179, s[6:7]
	s_mul_i32 s2, s3, 48
	v_add_u32_e32 v178, s2, v177
	v_add_u32_e32 v179, 0xfffff800, v178
	v_lshlrev_b32_e32 v178, 2, v178
	v_and_b32_e32 v179, 0x1fff, v179
	v_lshlrev_b32_e32 v179, 2, v179
	global_load_dword v208, v178, s[6:7]
	global_load_dword v250, v179, s[6:7]
	s_mul_i32 s2, s3, 49
	v_add_u32_e32 v178, s2, v177
	v_add_u32_e32 v179, 0xfffff800, v178
	v_lshlrev_b32_e32 v178, 2, v178
	v_and_b32_e32 v179, 0x1fff, v179
	v_lshlrev_b32_e32 v179, 2, v179
	global_load_dword v209, v178, s[6:7]
	global_load_dword v251, v179, s[6:7]
	s_mul_i32 s2, s3, 52
	v_add_u32_e32 v178, s2, v177
	v_add_u32_e32 v179, 0xfffff800, v178
	v_lshlrev_b32_e32 v178, 2, v178
	v_and_b32_e32 v179, 0x1fff, v179
; __device__ __forceinline__ void fft1_phase(KP P, int l) {
;     ...
;         f32x16 acc[4] = {};
; #pragma unroll
;         for (int s = 0; s < 8; ++s) {
;             const bf16x8_t bf = __builtin_bit_cast(bf16x8_t, bfr[s]);
; #pragma unroll
;             for (int mt = 0; mt < 4; ++mt) { const bf16x8_t af = *(const bf16x8_t*)(D1 + (32 * mt + r32) * 128 + 16 * s + 8 * hi);
;                 acc[mt] = __builtin_amdgcn_mfma_f32_32x32x16_bf16(af, bf, acc[mt], 0, 0, 0); }
	v_lshlrev_b32_e32 v179, 2, v179
	global_load_dword v210, v178, s[6:7]
	global_load_dword v252, v179, s[6:7]
	s_mul_i32 s2, s3, 53
	v_add_u32_e32 v178, s2, v177
	v_add_u32_e32 v179, 0xfffff800, v178
	v_lshlrev_b32_e32 v178, 2, v178
	v_and_b32_e32 v179, 0x1fff, v179
	v_lshlrev_b32_e32 v179, 2, v179
	global_load_dword v211, v178, s[6:7]
	global_load_dword v253, v179, s[6:7]
	s_mul_i32 s2, s3, 56
	v_add_u32_e32 v178, s2, v177
	v_add_u32_e32 v179, 0xfffff800, v178
	v_lshlrev_b32_e32 v178, 2, v178
	v_and_b32_e32 v179, 0x1fff, v179
	v_lshlrev_b32_e32 v179, 2, v179
	global_load_dword v212, v178, s[6:7]
	global_load_dword v218, v179, s[6:7]
	s_mul_i32 s2, s3, 57
	v_add_u32_e32 v178, s2, v177
	v_add_u32_e32 v179, 0xfffff800, v178
	v_lshlrev_b32_e32 v178, 2, v178
	v_and_b32_e32 v179, 0x1fff, v179
	v_lshlrev_b32_e32 v179, 2, v179
	global_load_dword v213, v178, s[6:7]
	global_load_dword v219, v179, s[6:7]
	s_mul_i32 s2, s3, 60
	v_add_u32_e32 v178, s2, v177
	v_add_u32_e32 v179, 0xfffff800, v178
	v_lshlrev_b32_e32 v178, 2, v178
	v_and_b32_e32 v179, 0x1fff, v179
	v_lshlrev_b32_e32 v179, 2, v179
	global_load_dword v214, v178, s[6:7]
	global_load_dword v220, v179, s[6:7]
	s_mul_i32 s2, s3, 61
	v_add_u32_e32 v178, s2, v177
	v_add_u32_e32 v179, 0xfffff800, v178
	v_lshlrev_b32_e32 v178, 2, v178
	v_and_b32_e32 v179, 0x1fff, v179
	v_lshlrev_b32_e32 v179, 2, v179
	global_load_dword v215, v178, s[6:7]
	global_load_dword v221, v179, s[6:7]
	s_add_u32 s2, s12, 0xc028000
	s_addc_u32 s3, s13, 0
	v_mov_b32_e32 v0, 0
	v_mov_b32_e32 v1, 0
	v_mov_b32_e32 v2, 0
	v_mov_b32_e32 v3, 0
	v_mov_b32_e32 v4, 0
	v_mov_b32_e32 v5, 0
	v_mov_b32_e32 v6, 0
	v_mov_b32_e32 v7, 0
	v_mov_b32_e32 v8, 0
	v_mov_b32_e32 v9, 0
	v_mov_b32_e32 v10, 0
	v_mov_b32_e32 v11, 0
	v_mov_b32_e32 v12, 0
	v_mov_b32_e32 v13, 0
	v_mov_b32_e32 v14, 0
	v_mov_b32_e32 v15, 0
	v_mov_b32_e32 v16, 0
	v_mov_b32_e32 v17, 0
	v_mov_b32_e32 v18, 0
	v_mov_b32_e32 v19, 0
	v_mov_b32_e32 v20, 0
	v_mov_b32_e32 v21, 0
	v_mov_b32_e32 v22, 0
	v_mov_b32_e32 v23, 0
	v_mov_b32_e32 v24, 0
	v_mov_b32_e32 v25, 0
	v_mov_b32_e32 v26, 0
	v_mov_b32_e32 v27, 0
	v_mov_b32_e32 v28, 0
	v_mov_b32_e32 v29, 0
	v_mov_b32_e32 v30, 0
	v_mov_b32_e32 v31, 0
	v_mov_b32_e32 v32, 0
	v_mov_b32_e32 v33, 0
	v_mov_b32_e32 v34, 0
	v_mov_b32_e32 v35, 0
	v_mov_b32_e32 v36, 0
	v_mov_b32_e32 v37, 0
	v_mov_b32_e32 v38, 0
	v_mov_b32_e32 v39, 0
	v_mov_b32_e32 v40, 0
	v_mov_b32_e32 v41, 0
	v_mov_b32_e32 v42, 0
	v_mov_b32_e32 v43, 0
	v_mov_b32_e32 v44, 0
	v_mov_b32_e32 v45, 0
	v_mov_b32_e32 v46, 0
	v_mov_b32_e32 v47, 0
	v_mov_b32_e32 v48, 0
	v_mov_b32_e32 v49, 0
	v_mov_b32_e32 v50, 0
	v_mov_b32_e32 v51, 0
	v_mov_b32_e32 v52, 0
	v_mov_b32_e32 v53, 0
	v_mov_b32_e32 v54, 0
	v_mov_b32_e32 v55, 0
	v_mov_b32_e32 v56, 0
	v_mov_b32_e32 v57, 0
	v_mov_b32_e32 v58, 0
	v_mov_b32_e32 v59, 0
	v_mov_b32_e32 v60, 0
	v_mov_b32_e32 v61, 0
	v_mov_b32_e32 v62, 0
	v_mov_b32_e32 v63, 0
	s_waitcnt vmcnt(63)
	v_mfma_f32_32x32x16_bf16 v[0:15], v[96:99], v[64:67], v[0:15]
	v_mfma_f32_32x32x16_bf16 v[16:31], v[100:103], v[64:67], v[16:31]
	v_mfma_f32_32x32x16_bf16 v[32:47], v[104:107], v[64:67], v[32:47]
	v_mfma_f32_32x32x16_bf16 v[48:63], v[108:111], v[64:67], v[48:63]
	s_waitcnt vmcnt(63)
	v_mfma_f32_32x32x16_bf16 v[0:15], v[112:115], v[68:71], v[0:15]
	v_mfma_f32_32x32x16_bf16 v[16:31], v[116:119], v[68:71], v[16:31]
	v_mfma_f32_32x32x16_bf16 v[32:47], v[120:123], v[68:71], v[32:47]
	v_mfma_f32_32x32x16_bf16 v[48:63], v[124:127], v[68:71], v[48:63]
	s_nop 1
	global_load_dwordx4 v[96:99], v171, s[2:3] offset:128
	global_load_dwordx4 v[100:103], v172, s[2:3] offset:128
	global_load_dwordx4 v[104:107], v173, s[2:3] offset:128
	global_load_dwordx4 v[108:111], v174, s[2:3] offset:128
	s_waitcnt vmcnt(63)
	v_mfma_f32_32x32x16_bf16 v[0:15], v[128:131], v[72:75], v[0:15]
	v_mfma_f32_32x32x16_bf16 v[16:31], v[132:135], v[72:75], v[16:31]
	v_mfma_f32_32x32x16_bf16 v[32:47], v[136:139], v[72:75], v[32:47]
	v_mfma_f32_32x32x16_bf16 v[48:63], v[140:143], v[72:75], v[48:63]
	s_nop 1
	global_load_dwordx4 v[112:115], v171, s[2:3] offset:160
	global_load_dwordx4 v[116:119], v172, s[2:3] offset:160
	global_load_dwordx4 v[120:123], v173, s[2:3] offset:160
	global_load_dwordx4 v[124:127], v174, s[2:3] offset:160
	s_waitcnt vmcnt(63)
	v_mfma_f32_32x32x16_bf16 v[0:15], v[148:151], v[76:79], v[0:15]
	v_mfma_f32_32x32x16_bf16 v[16:31], v[152:155], v[76:79], v[16:31]
	v_mfma_f32_32x32x16_bf16 v[32:47], v[156:159], v[76:79], v[32:47]
	v_mfma_f32_32x32x16_bf16 v[48:63], v[160:163], v[76:79], v[48:63]
	s_nop 1
	global_load_dwordx4 v[128:131], v171, s[2:3] offset:192
	global_load_dwordx4 v[132:135], v172, s[2:3] offset:192
	global_load_dwordx4 v[136:139], v173, s[2:3] offset:192
	global_load_dwordx4 v[140:143], v174, s[2:3] offset:192
	s_waitcnt vmcnt(8)
	v_mfma_f32_32x32x16_bf16 v[0:15], v[96:99], v[80:83], v[0:15]
	v_mfma_f32_32x32x16_bf16 v[16:31], v[100:103], v[80:83], v[16:31]
	v_mfma_f32_32x32x16_bf16 v[32:47], v[104:107], v[80:83], v[32:47]
	v_mfma_f32_32x32x16_bf16 v[48:63], v[108:111], v[80:83], v[48:63]
	s_nop 1
	global_load_dwordx4 v[148:151], v171, s[2:3] offset:224
	global_load_dwordx4 v[152:155], v172, s[2:3] offset:224
	global_load_dwordx4 v[156:159], v173, s[2:3] offset:224
	global_load_dwordx4 v[160:163], v174, s[2:3] offset:224
	s_waitcnt vmcnt(8)
	v_mfma_f32_32x32x16_bf16 v[0:15], v[112:115], v[84:87], v[0:15]
	v_mfma_f32_32x32x16_bf16 v[16:31], v[116:119], v[84:87], v[16:31]
	v_mfma_f32_32x32x16_bf16 v[32:47], v[120:123], v[84:87], v[32:47]
	v_mfma_f32_32x32x16_bf16 v[48:63], v[124:127], v[84:87], v[48:63]
	s_waitcnt vmcnt(4)
; __device__ __forceinline__ unsigned cvtpk(float lo, float hi) { const at_f32x2 v = {lo, hi}; const at_bf16x2 b = __builtin_convertvector(v, at_bf16x2); return __builtin_bit_cast(unsigned, b); }
; __device__ __forceinline__ void fft1_phase(KP P, int l) {
;     ...
;         unsigned* zs = (unsigned*)(ws + WS_ZS);
; #pragma unroll
;         for (int mt = 0; mt < 4; ++mt)
; #pragma unroll
;             for (int rq = 0; rq < 4; ++rq)
; #pragma unroll
;                 for (int e = 0; e < 2; ++e) {
;                     const int k1 = 16 * mt + 4 * rq + 2 * hi + e; const int idx = k1 * l2;
;                     const float ct = TAB[TAB_COS + idx], st = TAB[TAB_COS + ((idx - 2048) & 8191)];
;                     const float yr = acc[mt][4 * rq + 2 * e], yi = acc[mt][4 * rq + 2 * e + 1];
;                     zs[((size_t)(b * 64 + k1) * 128 + l2) * 256 + ch] = cvtpk(yr * ct + yi * st, yi * ct - yr * st);
;                 }
	v_mfma_f32_32x32x16_bf16 v[0:15], v[128:131], v[88:91], v[0:15]
	v_mfma_f32_32x32x16_bf16 v[16:31], v[132:135], v[88:91], v[16:31]
	v_mfma_f32_32x32x16_bf16 v[32:47], v[136:139], v[88:91], v[32:47]
	v_mfma_f32_32x32x16_bf16 v[48:63], v[140:143], v[88:91], v[48:63]
	s_waitcnt vmcnt(0)
	v_mfma_f32_32x32x16_bf16 v[0:15], v[148:151], v[92:95], v[0:15]
	v_mfma_f32_32x32x16_bf16 v[16:31], v[152:155], v[92:95], v[16:31]
	v_mfma_f32_32x32x16_bf16 v[32:47], v[156:159], v[92:95], v[32:47]
	v_mfma_f32_32x32x16_bf16 v[48:63], v[160:163], v[92:95], v[48:63]
	s_and_b32 s3, s26, 0x7f
	s_lshr_b32 s2, s26, 7
	s_lshl_b32 s2, s2, 13
	s_add_u32 s2, s2, s3
	s_lshl_b32 s2, s2, 10
	s_add_u32 s2, s2, 0xa100000
	s_add_u32 s14, s12, s2
	s_addc_u32 s15, s13, 0
	s_waitcnt vmcnt(0)
	s_nop 7
	s_nop 7
	v_mul_f32_e32 v178, v1, v226
	v_mul_f32_e32 v179, v0, v226
	v_fma_f32 v178, v0, v182, v178
	v_fma_f32 v179, v1, v182, -v179
	v_cvt_pk_bf16_f32 v180, v178, v179
	global_store_dword v175, v180, s[14:15]
	s_add_u32 s14, s14, 0x20000
	s_addc_u32 s15, s15, 0
	v_mul_f32_e32 v178, v3, v227
	v_mul_f32_e32 v179, v2, v227
	v_fma_f32 v178, v2, v183, v178
	v_fma_f32 v179, v3, v183, -v179
	v_cvt_pk_bf16_f32 v181, v178, v179
	global_store_dword v175, v181, s[14:15]
	s_add_u32 s14, s14, 0x60000
	s_addc_u32 s15, s15, 0
	v_mul_f32_e32 v178, v5, v228
	v_mul_f32_e32 v179, v4, v228
	v_fma_f32 v178, v4, v184, v178
	v_fma_f32 v179, v5, v184, -v179
	v_cvt_pk_bf16_f32 v180, v178, v179
	global_store_dword v175, v180, s[14:15]
	s_add_u32 s14, s14, 0x20000
	s_addc_u32 s15, s15, 0
	v_mul_f32_e32 v178, v7, v229
	v_mul_f32_e32 v179, v6, v229
	v_fma_f32 v178, v6, v185, v178
	v_fma_f32 v179, v7, v185, -v179
	v_cvt_pk_bf16_f32 v181, v178, v179
	global_store_dword v175, v181, s[14:15]
	s_add_u32 s14, s14, 0x60000
	s_addc_u32 s15, s15, 0
	v_mul_f32_e32 v178, v9, v230
	v_mul_f32_e32 v179, v8, v230
	v_fma_f32 v178, v8, v186, v178
	v_fma_f32 v179, v9, v186, -v179
	v_cvt_pk_bf16_f32 v180, v178, v179
	global_store_dword v175, v180, s[14:15]
	s_add_u32 s14, s14, 0x20000
	s_addc_u32 s15, s15, 0
	v_mul_f32_e32 v178, v11, v231
	v_mul_f32_e32 v179, v10, v231
	v_fma_f32 v178, v10, v187, v178
	v_fma_f32 v179, v11, v187, -v179
	v_cvt_pk_bf16_f32 v181, v178, v179
	global_store_dword v175, v181, s[14:15]
	s_add_u32 s14, s14, 0x60000
	s_addc_u32 s15, s15, 0
	v_mul_f32_e32 v178, v13, v232
	v_mul_f32_e32 v179, v12, v232
	v_fma_f32 v178, v12, v188, v178
	v_fma_f32 v179, v13, v188, -v179
	v_cvt_pk_bf16_f32 v180, v178, v179
	global_store_dword v175, v180, s[14:15]
	s_add_u32 s14, s14, 0x20000
	s_addc_u32 s15, s15, 0
	v_mul_f32_e32 v178, v15, v233
	v_mul_f32_e32 v179, v14, v233
	v_fma_f32 v178, v14, v189, v178
	v_fma_f32 v179, v15, v189, -v179
	v_cvt_pk_bf16_f32 v181, v178, v179
	global_store_dword v175, v181, s[14:15]
	s_add_u32 s14, s14, 0x60000
	s_addc_u32 s15, s15, 0
	v_mul_f32_e32 v178, v17, v234
	v_mul_f32_e32 v179, v16, v234
	v_fma_f32 v178, v16, v190, v178
	v_fma_f32 v179, v17, v190, -v179
	v_cvt_pk_bf16_f32 v180, v178, v179
	global_store_dword v175, v180, s[14:15]
	s_add_u32 s14, s14, 0x20000
	s_addc_u32 s15, s15, 0
	v_mul_f32_e32 v178, v19, v235
	v_mul_f32_e32 v179, v18, v235
	v_fma_f32 v178, v18, v191, v178
	v_fma_f32 v179, v19, v191, -v179
	v_cvt_pk_bf16_f32 v181, v178, v179
	global_store_dword v175, v181, s[14:15]
	s_add_u32 s14, s14, 0x60000
	s_addc_u32 s15, s15, 0
	v_mul_f32_e32 v178, v21, v236
	v_mul_f32_e32 v179, v20, v236
	v_fma_f32 v178, v20, v192, v178
	v_fma_f32 v179, v21, v192, -v179
	v_cvt_pk_bf16_f32 v180, v178, v179
	global_store_dword v175, v180, s[14:15]
	s_add_u32 s14, s14, 0x20000
	s_addc_u32 s15, s15, 0
	v_mul_f32_e32 v178, v23, v237
	v_mul_f32_e32 v179, v22, v237
	v_fma_f32 v178, v22, v193, v178
	v_fma_f32 v179, v23, v193, -v179
	v_cvt_pk_bf16_f32 v181, v178, v179
	global_store_dword v175, v181, s[14:15]
	s_add_u32 s14, s14, 0x60000
	s_addc_u32 s15, s15, 0
	v_mul_f32_e32 v178, v25, v238
	v_mul_f32_e32 v179, v24, v238
	v_fma_f32 v178, v24, v194, v178
	v_fma_f32 v179, v25, v194, -v179
	v_cvt_pk_bf16_f32 v180, v178, v179
	global_store_dword v175, v180, s[14:15]
	s_add_u32 s14, s14, 0x20000
	s_addc_u32 s15, s15, 0
	v_mul_f32_e32 v178, v27, v239
	v_mul_f32_e32 v179, v26, v239
	v_fma_f32 v178, v26, v195, v178
	v_fma_f32 v179, v27, v195, -v179
	v_cvt_pk_bf16_f32 v181, v178, v179
	global_store_dword v175, v181, s[14:15]
	s_add_u32 s14, s14, 0x60000
	s_addc_u32 s15, s15, 0
	v_mul_f32_e32 v178, v29, v240
	v_mul_f32_e32 v179, v28, v240
	v_fma_f32 v178, v28, v196, v178
	v_fma_f32 v179, v29, v196, -v179
	v_cvt_pk_bf16_f32 v180, v178, v179
; __device__ __forceinline__ unsigned cvtpk(float lo, float hi) { const at_f32x2 v = {lo, hi}; const at_bf16x2 b = __builtin_convertvector(v, at_bf16x2); return __builtin_bit_cast(unsigned, b); }
; __device__ __forceinline__ void fft1_phase(KP P, int l) {
;     ...
;     for (int it = bid_; it < 256; it += gridDim.x) {
;     ...
;         unsigned* zs = (unsigned*)(ws + WS_ZS);
; #pragma unroll
;         for (int mt = 0; mt < 4; ++mt)
; #pragma unroll
;             for (int rq = 0; rq < 4; ++rq)
; #pragma unroll
;                 for (int e = 0; e < 2; ++e) {
;                     const int k1 = 16 * mt + 4 * rq + 2 * hi + e; const int idx = k1 * l2;
;                     const float ct = TAB[TAB_COS + idx], st = TAB[TAB_COS + ((idx - 2048) & 8191)];
;                     const float yr = acc[mt][4 * rq + 2 * e], yi = acc[mt][4 * rq + 2 * e + 1];
;                     zs[((size_t)(b * 64 + k1) * 128 + l2) * 256 + ch] = cvtpk(yr * ct + yi * st, yi * ct - yr * st);
;                 }
	global_store_dword v175, v180, s[14:15]
	s_add_u32 s14, s14, 0x20000
	s_addc_u32 s15, s15, 0
	v_mul_f32_e32 v178, v31, v241
	v_mul_f32_e32 v179, v30, v241
	v_fma_f32 v178, v30, v197, v178
	v_fma_f32 v179, v31, v197, -v179
	v_cvt_pk_bf16_f32 v181, v178, v179
	global_store_dword v175, v181, s[14:15]
	s_add_u32 s14, s14, 0x60000
	s_addc_u32 s15, s15, 0
	v_mul_f32_e32 v178, v33, v242
	v_mul_f32_e32 v179, v32, v242
	v_fma_f32 v178, v32, v200, v178
	v_fma_f32 v179, v33, v200, -v179
	v_cvt_pk_bf16_f32 v180, v178, v179
	global_store_dword v175, v180, s[14:15]
	s_add_u32 s14, s14, 0x20000
	s_addc_u32 s15, s15, 0
	v_mul_f32_e32 v178, v35, v243
	v_mul_f32_e32 v179, v34, v243
	v_fma_f32 v178, v34, v201, v178
	v_fma_f32 v179, v35, v201, -v179
	v_cvt_pk_bf16_f32 v181, v178, v179
	global_store_dword v175, v181, s[14:15]
	s_add_u32 s14, s14, 0x60000
	s_addc_u32 s15, s15, 0
	v_mul_f32_e32 v178, v37, v244
	v_mul_f32_e32 v179, v36, v244
	v_fma_f32 v178, v36, v202, v178
	v_fma_f32 v179, v37, v202, -v179
	v_cvt_pk_bf16_f32 v180, v178, v179
	global_store_dword v175, v180, s[14:15]
	s_add_u32 s14, s14, 0x20000
	s_addc_u32 s15, s15, 0
	v_mul_f32_e32 v178, v39, v245
	v_mul_f32_e32 v179, v38, v245
	v_fma_f32 v178, v38, v203, v178
	v_fma_f32 v179, v39, v203, -v179
	v_cvt_pk_bf16_f32 v181, v178, v179
	global_store_dword v175, v181, s[14:15]
	s_add_u32 s14, s14, 0x60000
	s_addc_u32 s15, s15, 0
	v_mul_f32_e32 v178, v41, v246
	v_mul_f32_e32 v179, v40, v246
	v_fma_f32 v178, v40, v204, v178
	v_fma_f32 v179, v41, v204, -v179
	v_cvt_pk_bf16_f32 v180, v178, v179
	global_store_dword v175, v180, s[14:15]
	s_add_u32 s14, s14, 0x20000
	s_addc_u32 s15, s15, 0
	v_mul_f32_e32 v178, v43, v247
	v_mul_f32_e32 v179, v42, v247
	v_fma_f32 v178, v42, v205, v178
	v_fma_f32 v179, v43, v205, -v179
	v_cvt_pk_bf16_f32 v181, v178, v179
	global_store_dword v175, v181, s[14:15]
	s_add_u32 s14, s14, 0x60000
	s_addc_u32 s15, s15, 0
	v_mul_f32_e32 v178, v45, v248
	v_mul_f32_e32 v179, v44, v248
	v_fma_f32 v178, v44, v206, v178
	v_fma_f32 v179, v45, v206, -v179
	v_cvt_pk_bf16_f32 v180, v178, v179
	global_store_dword v175, v180, s[14:15]
	s_add_u32 s14, s14, 0x20000
	s_addc_u32 s15, s15, 0
	v_mul_f32_e32 v178, v47, v249
	v_mul_f32_e32 v179, v46, v249
	v_fma_f32 v178, v46, v207, v178
	v_fma_f32 v179, v47, v207, -v179
	v_cvt_pk_bf16_f32 v181, v178, v179
	global_store_dword v175, v181, s[14:15]
	s_add_u32 s14, s14, 0x60000
	s_addc_u32 s15, s15, 0
	v_mul_f32_e32 v178, v49, v250
	v_mul_f32_e32 v179, v48, v250
	v_fma_f32 v178, v48, v208, v178
	v_fma_f32 v179, v49, v208, -v179
	v_cvt_pk_bf16_f32 v180, v178, v179
	global_store_dword v175, v180, s[14:15]
	s_add_u32 s14, s14, 0x20000
	s_addc_u32 s15, s15, 0
	v_mul_f32_e32 v178, v51, v251
	v_mul_f32_e32 v179, v50, v251
	v_fma_f32 v178, v50, v209, v178
	v_fma_f32 v179, v51, v209, -v179
	v_cvt_pk_bf16_f32 v181, v178, v179
	global_store_dword v175, v181, s[14:15]
	s_add_u32 s14, s14, 0x60000
	s_addc_u32 s15, s15, 0
	v_mul_f32_e32 v178, v53, v252
	v_mul_f32_e32 v179, v52, v252
	v_fma_f32 v178, v52, v210, v178
	v_fma_f32 v179, v53, v210, -v179
	v_cvt_pk_bf16_f32 v180, v178, v179
	global_store_dword v175, v180, s[14:15]
	s_add_u32 s14, s14, 0x20000
	s_addc_u32 s15, s15, 0
	v_mul_f32_e32 v178, v55, v253
	v_mul_f32_e32 v179, v54, v253
	v_fma_f32 v178, v54, v211, v178
	v_fma_f32 v179, v55, v211, -v179
	v_cvt_pk_bf16_f32 v181, v178, v179
	global_store_dword v175, v181, s[14:15]
	s_add_u32 s14, s14, 0x60000
	s_addc_u32 s15, s15, 0
	v_mul_f32_e32 v178, v57, v218
	v_mul_f32_e32 v179, v56, v218
	v_fma_f32 v178, v56, v212, v178
	v_fma_f32 v179, v57, v212, -v179
	v_cvt_pk_bf16_f32 v180, v178, v179
	global_store_dword v175, v180, s[14:15]
	s_add_u32 s14, s14, 0x20000
	s_addc_u32 s15, s15, 0
	v_mul_f32_e32 v178, v59, v219
	v_mul_f32_e32 v179, v58, v219
	v_fma_f32 v178, v58, v213, v178
	v_fma_f32 v179, v59, v213, -v179
	v_cvt_pk_bf16_f32 v181, v178, v179
	global_store_dword v175, v181, s[14:15]
	s_add_u32 s14, s14, 0x60000
	s_addc_u32 s15, s15, 0
	v_mul_f32_e32 v178, v61, v220
	v_mul_f32_e32 v179, v60, v220
	v_fma_f32 v178, v60, v214, v178
	v_fma_f32 v179, v61, v214, -v179
	v_cvt_pk_bf16_f32 v180, v178, v179
	global_store_dword v175, v180, s[14:15]
	s_add_u32 s14, s14, 0x20000
	s_addc_u32 s15, s15, 0
	v_mul_f32_e32 v178, v63, v221
	v_mul_f32_e32 v179, v62, v221
	v_fma_f32 v178, v62, v215, v178
	v_fma_f32 v179, v63, v215, -v179
	v_cvt_pk_bf16_f32 v181, v178, v179
	global_store_dword v175, v181, s[14:15]
	s_load_dword s2, s[72:73], 0x0
	s_waitcnt lgkmcnt(0)
	s_add_i32 s26, s26, s2
	s_branch .Lf1_item
